# adds: P4 tail tiles run before its GEMM units (same as P6)
# speedup vs baseline: 1.0322x; 1.0072x over previous
; template <class Epi, bool TWO, bool PERM, bool BIAS = false>
; __device__ __forceinline__ void gemm_phase(LAS unsigned char* lds, const Gemm g, const StaticOrder& S, const Epi& E, const int tid) {
;     const int wid = __builtin_amdgcn_readfirstlane(tid >> 6), lane = tid & 63, wr = wid >> 2, wc = wid & 3, fr = lane & 15, fq = lane >> 4;
;     const int K = g.K, nt = g.nt;
;     unsigned voffA[2], voffB[2];
; #pragma unroll
;     for (int i = 0; i < 2; ++i) { int R, C; stage_rc(tid * 16 + i * 8192, R, C); const int Rb = PERM ? ((R & ~31) + perm32(R & 31)) : R;
;         voffA[i] = (unsigned)(R * K + C) * 2u; voffB[i] = (unsigned)(Rb * K + C) * 2u; }
;     const size_t kstep = (size_t)(BK * 2);
;     const size_t hstep = (size_t)HALF * K * 2;
;     const size_t tstep = 2 * hstep;
;     const unsigned ldsw = (unsigned)wid * 1024u;
;     const int aoff = lds_byte(wr * 64 + fr, fq * 8), boff = lds_byte(wc * 32 + fr, fq * 8);
;     ...
;     Unit cur, nxt; int ui = 0;
;     if (!S.next(0, cur)) return;
;     f32x4 acc[2][2][4][2], binit[2][2];
; #pragma unroll
;     for (int b = 0; b < 2; ++b)
; #pragma unroll
;         for (int n = 0; n < 2; ++n) binit[b][n] = (f32x4){0.f, 0.f, 0.f, 0.f};
;     if constexpr (BIAS) E.load_bias(cur, wc, fq, binit);
; #pragma unroll
;     for (int a = 0; a < 2; ++a)
; #pragma unroll
;         for (int b = 0; b < 2; ++b)
; #pragma unroll
;             for (int m = 0; m < 4; ++m)
; #pragma unroll
;                 for (int n = 0; n < 2; ++n) acc[a][b][m][n] = binit[b][n];
;     bf16x8 At[4][2], B0[2][2], B1[2][2];
;     const char* cA = (const char*)g.A + (size_t)cur.pm * tstep; const char* cB = (const char*)g.Bt + (size_t)cur.pn * tstep;
;     PG8_STAGEB(PG8_SB(0, 0), cB); PG8_STAGEB(PG8_SB(0, 1), cB + hstep); PG8_STAGE(PG8_SA(0, 0), cA); PG8_STAGE(PG8_SA(0, 1), cA + hstep);
;     if (wr == 1) PG8_BAR;
; __global__ __launch_bounds__(512, 2) void fwd_mega(Args a0_) {
;     ...
;     for (int pi = a0.ph_lo; pi < a0.ph_hi; ++pi) {
;         const int ph = kSeq[pi];
;         Args a = a0;
;         int tid = threadIdx.x; asm volatile("" : "+v"(tid));
;         const int wave = __builtin_amdgcn_readfirstlane(tid >> 6), lane = tid & 63, gw = blockIdx.x * 8 + wave, ngw = G * 8;
;         bf16_t* PA = (bf16_t*)(a.ws + WS_PA);
;         if (ph == 0) {
;             phase0(a, lds, gw, ngw, wave, lane);
;         } else if (ph == 2) {
.LBB0_22:
	s_mov_b64 s[0:1], s[40:41]
	s_mov_b32 s3, s43
	v_writelane_b32 v255, s0, 11
	s_mov_b32 s24, s42
	s_ashr_i32 s25, s42, 31
	v_writelane_b32 v255, s1, 12
	v_writelane_b32 v255, s2, 13
	v_writelane_b32 v255, s3, 14
	s_lshl_b64 s[0:1], s[24:25], 2
	s_getpc_b64 s[20:21]
	s_add_u32 s20, s20, _ZL4kSeq@rel32@lo+4
	s_addc_u32 s21, s21, _ZL4kSeq@rel32@hi+12
	s_add_u32 s0, s20, s0
	v_mov_b32_e32 v216, v187
	s_addc_u32 s1, s21, s1
	s_load_dword s2, s[0:1], 0x0
	v_readfirstlane_b32 s8, v216
	s_ashr_i32 s0, s8, 6
	s_add_i32 s87, s0, s72
	v_writelane_b32 v255, s0, 15
	s_waitcnt lgkmcnt(0)
	s_mov_b32 s94, s2
	s_cmp_lt_i32 s2, 3
	s_mov_b64 s[2:3], 0
	v_writelane_b32 v255, s2, 16
	v_and_b32_e32 v186, 63, v216
	s_mov_b64 s[0:1], -1
	v_writelane_b32 v255, s3, 17
	s_mov_b32 s2, s42
	v_writelane_b32 v255, s2, 18
	s_nop 1
	v_writelane_b32 v255, s3, 19
	s_cbranch_scc1 .LBB0_467
	s_cmp_gt_i32 s94, 3
	s_cbranch_scc0 .LBB0_46
	s_cmp_eq_u32 s94, 4
	s_mov_b64 s[0:1], -1
	s_cbranch_scc0 .LBB0_52
	s_branch .LBB0_48
.Lsb_gemm4:
	v_readlane_b32 s0, v252, 6
	v_readlane_b32 s1, v252, 7
	s_andn2_b64 vcc, exec, s[0:1]
	v_readfirstlane_b32 s20, v216
	s_cbranch_vccnz .LBB0_51
	s_waitcnt vmcnt(0)
	v_lshlrev_b32_e32 v3, 4, v216
	v_add_u32_e32 v1, 0x2000, v3
	v_ashrrev_i32_e32 v0, 31, v1
	v_lshrrev_b32_e32 v0, 22, v0
	v_add_u32_e32 v0, v1, v0
	v_ashrrev_i32_e32 v0, 10, v0
	v_mul_i32_i24_e32 v2, 0x400, v0
	v_sub_u32_e32 v1, v1, v2
	v_lshrrev_b32_e32 v2, 4, v1
	v_bitop3_b32 v2, v2, v1, 32 bitop3:0x6c
	v_ashrrev_i32_e32 v1, 31, v2
	v_lshrrev_b32_e32 v1, 26, v1
	v_add_u32_e32 v4, v2, v1
	v_lshlrev_b32_e32 v5, 3, v0
	v_ashrrev_i32_e32 v1, 6, v4
	v_and_b32_e32 v5, -16, v5
	v_add_u32_e32 v5, v1, v5
	v_and_b32_e32 v6, 3, v1
	s_mov_b32 s0, 0xfffe0
	v_lshrrev_b32_e32 v7, 2, v5
	v_lshlrev_b32_e32 v8, 1, v5
	v_and_b32_e32 v4, 0xc0, v4
	v_and_or_b32 v6, v5, s0, v6
	v_and_b32_e32 v7, 4, v7
	v_and_b32_e32 v8, 24, v8
	v_sub_u32_e32 v2, v2, v4
	v_or3_b32 v6, v6, v7, v8
	v_lshlrev_b32_e32 v7, 5, v0
	v_ashrrev_i16_sdwa v2, v214, sext(v2) dst_sel:DWORD dst_unused:UNUSED_PAD src0_sel:DWORD src1_sel:BYTE_0
	v_and_b32_e32 v7, 32, v7
	v_bfe_i32 v2, v2, 0, 16
	v_add_lshl_u32 v4, v7, v2, 1
	v_lshl_add_u32 v176, v6, 12, v4
	v_lshl_add_u32 v178, v5, 12, v4
	v_bfe_i32 v4, v216, 27, 1
	v_lshrrev_b32_e32 v4, 22, v4
	v_add_u32_e32 v4, v3, v4
	v_and_b32_e32 v4, 0xfffffc00, v4
	v_sub_u32_e32 v3, v3, v4
	v_lshrrev_b32_e32 v4, 4, v3
	v_bitop3_b32 v5, v4, v3, 32 bitop3:0x6c
	v_ashrrev_i32_e32 v4, 31, v216
	v_lshrrev_b32_e32 v4, 26, v4
	v_ashrrev_i32_e32 v3, 31, v5
	v_add_u32_e32 v4, v216, v4
	v_lshrrev_b32_e32 v3, 26, v3
	v_ashrrev_i32_e32 v4, 6, v4
	v_add_u32_e32 v6, v5, v3
	v_lshlrev_b32_e32 v7, 3, v4
	v_ashrrev_i32_e32 v3, 6, v6
	v_and_b32_e32 v7, -16, v7
	v_add_u32_e32 v7, v3, v7
	v_and_b32_e32 v8, 3, v3
	v_lshrrev_b32_e32 v9, 2, v7
	v_lshlrev_b32_e32 v10, 1, v7
	v_and_b32_e32 v6, 0xc0, v6
	v_and_or_b32 v8, v7, s0, v8
	v_and_b32_e32 v9, 4, v9
	v_and_b32_e32 v10, 24, v10
	v_sub_u32_e32 v5, v5, v6
	s_ashr_i32 s21, s20, 6
	v_or3_b32 v8, v8, v9, v10
	v_lshlrev_b32_e32 v9, 5, v4
	v_ashrrev_i16_sdwa v5, v214, sext(v5) dst_sel:DWORD dst_unused:UNUSED_PAD src0_sel:DWORD src1_sel:BYTE_0
	s_lshl_b32 s26, s21, 10
	v_and_b32_e32 v9, 32, v9
	v_bfe_i32 v5, v5, 0, 16
	v_add_lshl_u32 v6, v9, v5, 1
	s_add_i32 s27, s26, 0
	v_readlane_b32 s0, v254, 11
	v_lshl_add_u32 v180, v8, 12, v6
	s_add_i32 m0, s27, 0x10000
	v_readlane_b32 s1, v254, 12
	v_lshl_add_u32 v188, v7, 12, v6
	s_add_i32 s28, s27, 0x2000
	s_add_i32 s29, s27, 0x4000
	s_add_i32 s34, s27, 0x6000
	s_ashr_i32 s22, s20, 8
	global_load_lds_dwordx4 v180, s[0:1]
	s_add_i32 m0, s27, 0x12000
	s_nop 0
	global_load_lds_dwordx4 v176, s[0:1]
	v_readlane_b32 s0, v254, 5
	s_add_i32 m0, s27, 0x14000
	v_readlane_b32 s1, v254, 6
	s_nop 4
	global_load_lds_dwordx4 v180, s[0:1]
	s_add_i32 m0, s27, 0x16000
	s_cmp_eq_u32 s22, 1
	global_load_lds_dwordx4 v176, s[0:1]
	v_readlane_b32 s0, v254, 7
	s_mov_b32 m0, s27
	v_readlane_b32 s1, v254, 8
	s_nop 4
	global_load_lds_dwordx4 v188, s[0:1]
	s_mov_b32 m0, s28
	s_nop 0
	global_load_lds_dwordx4 v178, s[0:1]
	v_readlane_b32 s0, v254, 9
	s_mov_b32 m0, s29
	v_readlane_b32 s1, v254, 10
	s_nop 4
	global_load_lds_dwordx4 v188, s[0:1]
	s_mov_b32 m0, s34
	s_nop 0
	global_load_lds_dwordx4 v178, s[0:1]
	s_cselect_b64 s[0:1], -1, 0
	s_cmp_lg_u32 s22, 1
	s_cbranch_scc1 .LBB0_28
	s_barrier

; #define LAS __attribute__((address_space(3)))
; template <int MODE  >
; __device__ __forceinline__ void mini_tile(const Args& a, LAS unsigned char* lds, int tile, int tid) {
;     const int wave = __builtin_amdgcn_readfirstlane(tid >> 6), lane = tid & 63, r = lane & 31, h = lane >> 5;
;     const int rb = tile >> 4, cb = tile & 15, R0 = TAIL0 + 32 * rb, C0 = 64 * cb, k0 = 128 * wave;
;     constexpr int NP = MODE == 0 ? 2 : 1;
;     const bf16_t* PA = (const bf16_t*)(a.ws + WS_PA);
;     constexpr int LDA = MODE == 0 ? LDY : DM;
;     const bf16_t* A1 = (MODE == 0 ? (const bf16_t*)(a.ws + WS_YC) : (const bf16_t*)(a.ws + WS_MM)) + (size_t)(R0 + r) * LDA + k0 + 8 * h;
;     const bf16_t* B1 = (MODE == 0 ? (const bf16_t*)(a.ws + WS_WCO) : (const bf16_t*)(a.ws + WS_WO)) + (size_t)(C0 + r) * LDA + k0 + 8 * h;
;     const bf16_t* A2 = A1 + DM;
;     const bf16_t* B2 = B1 + DM;
;     f32x16 acc[NP][2];
; #pragma unroll
;     for (int p = 0; p < NP; ++p)
; #pragma unroll
;         for (int c = 0; c < 2; ++c)
; #pragma unroll
;             for (int i = 0; i < 16; ++i) acc[p][c][i] = 0.f;
; #pragma unroll
;     for (int s = 0; s < 8; ++s) {
;         const bf16x8 a1 = *(const bf16x8*)(A1 + 16 * s), b10 = *(const bf16x8*)(B1 + 16 * s), b11 = *(const bf16x8*)(B1 + 32 * LDA + 16 * s);
;         acc[0][0] = __builtin_amdgcn_mfma_f32_32x32x16_bf16(a1, b10, acc[0][0], 0, 0, 0);
;         acc[0][1] = __builtin_amdgcn_mfma_f32_32x32x16_bf16(a1, b11, acc[0][1], 0, 0, 0);
;         if (MODE == 0) {
;             const bf16x8 a2 = *(const bf16x8*)(A2 + 16 * s), b20 = *(const bf16x8*)(B2 + 16 * s), b21 = *(const bf16x8*)(B2 + 32 * LDA + 16 * s);
;             acc[NP - 1][0] = __builtin_amdgcn_mfma_f32_32x32x16_bf16(a2, b20, acc[NP - 1][0], 0, 0, 0);
;             acc[NP - 1][1] = __builtin_amdgcn_mfma_f32_32x32x16_bf16(a2, b21, acc[NP - 1][1], 0, 0, 0);
;         }
;     }
;     LAS float* red = (LAS float*)lds;
; #pragma unroll
;     for (int p = 0; p < NP; ++p)
; #pragma unroll
;         for (int c = 0; c < 2; ++c)
; #pragma unroll
;             for (int i = 0; i < 16; ++i) red[((((wave * NP + p) * 2 + c) * 16 + i) << 6) + lane] = acc[p][c][i];
;     __syncthreads();
; #pragma unroll
;     for (int j = 0; j < 4; ++j) {
;         const int e = tid + 512 * j, c = e >> 10, i = (e >> 6) & 15, l = e & 63;
;         float s1 = 0.f, s2 = 0.f;
; #pragma unroll
.LBB0_46:
	s_mov_b64 s[2:3], 0
	v_writelane_b32 v255, s2, 16
	s_nop 1
	v_writelane_b32 v255, s3, 17
	s_and_b64 vcc, exec, s[0:1]
	s_cbranch_vccnz .LBB0_53
	s_branch .LBB0_466
.LBB0_47:
	s_waitcnt vmcnt(0)
	s_barrier
	s_branch .LBB0_51
.LBB0_48:
	v_readlane_b32 s0, v252, 8
	v_readlane_b32 s1, v252, 9
	s_andn2_b64 vcc, exec, s[0:1]
	s_mov_b32 s2, 0x20000
	s_mov_b32 s3, 0x18600000
	s_mov_b32 s26, 0x1c700000
	s_cbranch_vccnz .Lsb_gemm4
	s_waitcnt vmcnt(0)
	v_ashrrev_i32_e32 v2, 10, v216
	v_lshrrev_b32_e32 v1, 3, v216
	v_lshlrev_b32_e32 v4, 12, v2
	v_lshrrev_b32_e32 v12, 5, v216
	v_lshlrev_b32_e32 v78, 5, v2
	v_add_u32_e32 v2, 0x200, v216
	v_and_b32_e32 v1, 4, v1
	v_and_b32_e32 v12, 24, v12
	v_bfe_u32 v13, v216, 6, 2
	v_lshrrev_b32_e32 v18, 5, v2
	v_or3_b32 v77, v13, v12, v1
	v_ashrrev_i32_e32 v12, 10, v2
	v_lshlrev_b32_e32 v13, 2, v2
	v_and_b32_e32 v18, 24, v18
	v_bfe_u32 v2, v2, 6, 2
	v_or3_b32 v84, v2, v18, v1
	v_add_u32_e32 v2, 0x400, v216
	v_lshrrev_b32_e32 v23, 5, v2
	v_lshlrev_b32_e32 v14, 12, v12
	v_lshlrev_b32_e32 v85, 5, v12
	v_ashrrev_i32_e32 v12, 10, v2
	v_lshlrev_b32_e32 v18, 2, v2
	v_and_b32_e32 v23, 24, v23
	v_bfe_u32 v2, v2, 6, 2
	v_lshl_add_u32 v71, v186, 2, 0
	v_lshlrev_b32_e32 v3, 2, v216
	v_or3_b32 v91, v2, v23, v1
	v_add_u32_e32 v2, 0x600, v216
	v_and_b32_e32 v3, 0xf00, v3
	v_add_u32_e32 v5, v71, v4
	v_lshlrev_b32_e32 v19, 12, v12
	v_lshlrev_b32_e32 v92, 5, v12
	v_ashrrev_i32_e32 v12, 10, v2
	v_add_u32_e32 v72, v5, v3
	v_add_u32_e32 v5, 0x10000, v71
	v_add_u32_e32 v7, 0x14000, v71
	v_add_u32_e32 v9, 0x18000, v71
	v_add_u32_e32 v11, 0x1c000, v71
	v_and_b32_e32 v13, 0xf00, v13
	v_add_u32_e32 v15, v71, v14
	v_and_b32_e32 v18, 0xf00, v18
	v_add_u32_e32 v20, v71, v19
	v_lshlrev_b32_e32 v23, 2, v2
	v_lshlrev_b32_e32 v24, 12, v12
	v_lshrrev_b32_e32 v0, 2, v216
	v_add_u32_e32 v6, v5, v4
	v_add_u32_e32 v8, v7, v4
	v_add_u32_e32 v10, v9, v4
	v_add_u32_e32 v4, v11, v4
	v_add_u32_e32 v79, v15, v13
	v_add_u32_e32 v15, v5, v14
	v_add_u32_e32 v16, v7, v14
	v_add_u32_e32 v17, v9, v14
	v_add_u32_e32 v14, v11, v14
	v_add_u32_e32 v86, v20, v18
	v_add_u32_e32 v20, v5, v19
	v_add_u32_e32 v21, v7, v19
	v_add_u32_e32 v22, v9, v19
	v_add_u32_e32 v19, v11, v19
	v_and_b32_e32 v23, 0xf00, v23
	v_add_u32_e32 v25, v71, v24
	v_add_u32_e32 v5, v5, v24
	v_add_u32_e32 v7, v7, v24
	v_add_u32_e32 v9, v9, v24
	v_add_u32_e32 v11, v11, v24
	v_lshrrev_b32_e32 v24, 5, v2
	v_and_b32_e32 v0, 8, v0
	v_add_u32_e32 v93, v25, v23
	v_and_b32_e32 v24, 24, v24
	v_bfe_u32 v2, v2, 6, 2
	v_and_b32_e32 v70, 31, v216
	v_add_u32_e32 v73, 0x12000, v72
	v_add_u32_e32 v74, 0x16000, v72
	v_add_u32_e32 v75, 0x1a000, v72
	v_add_u32_e32 v76, 0x1e000, v72
	v_add_u32_e32 v80, 0x12000, v79
	v_add_u32_e32 v81, 0x16000, v79
	v_add_u32_e32 v82, 0x1a000, v79
	v_add_u32_e32 v83, 0x1e000, v79
	v_add_u32_e32 v87, 0x12000, v86
	v_add_u32_e32 v88, 0x16000, v86
	v_add_u32_e32 v89, 0x1a000, v86
	v_add_u32_e32 v90, 0x1e000, v86
	v_add_u32_e32 v94, 0x12000, v93
	v_add_u32_e32 v95, 0x16000, v93
	v_add_u32_e32 v96, 0x1a000, v93
	v_add_u32_e32 v97, 0x1e000, v93
	v_or3_b32 v98, v2, v24, v1
	v_lshlrev_b32_e32 v99, 5, v12
	v_lshlrev_b32_e32 v180, 1, v0
	v_add_u32_e32 v100, v6, v3
	v_add_u32_e32 v101, v8, v3
	v_add_u32_e32 v102, v10, v3
	v_add_u32_e32 v103, v4, v3
	v_add_u32_e32 v104, v15, v13
	v_add_u32_e32 v105, v16, v13
	v_add_u32_e32 v106, v17, v13
	v_add_u32_e32 v107, v14, v13
	v_add_u32_e32 v108, v20, v18
	v_add_u32_e32 v109, v21, v18
	v_add_u32_e32 v110, v22, v18
	v_add_u32_e32 v111, v19, v18
	v_add_u32_e32 v112, v5, v23
	v_add_u32_e32 v113, v7, v23
	v_add_u32_e32 v114, v9, v23
	v_add_u32_e32 v115, v11, v23
	v_readlane_b32 s20, v254, 41
	v_readlane_b32 s21, v254, 40
	s_mov_b32 s22, s81
.LBB0_50:
	s_and_b32 s23, s21, 0xffffffe0
	v_readfirstlane_b32 s0, v216
	s_add_i32 s23, s23, 0x8000
	s_ashr_i32 s24, s0, 6
	v_or_b32_e32 v0, s23, v70
	s_lshl_b32 s0, s24, 7
	v_ashrrev_i32_e32 v1, 31, v0
	v_lshlrev_b64 v[0:1], 12, v[0:1]
	s_ashr_i32 s1, s0, 31
	s_and_b32 s25, s20, 0x3c0
	v_lshl_add_u64 v[0:1], s[76:77], 0, v[0:1]
	s_lshl_b64 s[0:1], s[0:1], 1
	v_lshl_add_u64 v[0:1], v[0:1], 0, s[0:1]
	v_or_b32_e32 v116, s25, v70
	v_lshl_add_u64 v[66:67], v[0:1], 0, v[180:181]
	v_lshlrev_b32_e32 v0, 12, v116
	v_mov_b32_e32 v1, v181
	v_lshl_add_u64 v[0:1], s[78:79], 0, v[0:1]
	v_lshl_add_u64 v[0:1], v[0:1], 0, s[0:1]
	v_lshl_add_u64 v[68:69], v[0:1], 0, v[180:181]
	v_add_co_u32_e32 v64, vcc, s2, v68
	s_nop 1
	v_addc_co_u32_e32 v65, vcc, 0, v69, vcc
	s_add_i32 s22, s22, s84
	s_add_i32 s21, s21, s91
	s_add_i32 s20, s20, s95
	s_cmpk_gt_i32 s22, 0x9f
	global_load_dwordx4 v[132:135], v[66:67], off
	global_load_dwordx4 v[136:139], v[68:69], off
	global_load_dwordx4 v[140:143], v[64:65], off
	global_load_dwordx4 v[144:147], v[66:67], off offset:2048
	global_load_dwordx4 v[148:151], v[68:69], off offset:2048
	global_load_dwordx4 v[152:155], v[64:65], off offset:2048
	global_load_dwordx4 v[156:159], v[66:67], off offset:32
	global_load_dwordx4 v[160:163], v[68:69], off offset:32
	global_load_dwordx4 v[164:167], v[64:65], off offset:32
	global_load_dwordx4 v[168:171], v[66:67], off offset:2080
	global_load_dwordx4 v[172:175], v[68:69], off offset:2080
	global_load_dwordx4 v[176:179], v[64:65], off offset:2080
	global_load_dwordx4 v[188:191], v[66:67], off offset:64
	global_load_dwordx4 v[192:195], v[68:69], off offset:64
	global_load_dwordx4 v[196:199], v[64:65], off offset:64
	global_load_dwordx4 v[200:203], v[66:67], off offset:2112
	global_load_dwordx4 v[204:207], v[68:69], off offset:2112
	global_load_dwordx4 v[208:211], v[64:65], off offset:2112
	global_load_dwordx4 v[220:223], v[66:67], off offset:96
	global_load_dwordx4 v[224:227], v[68:69], off offset:96
	global_load_dwordx4 v[228:231], v[64:65], off offset:96
	global_load_dwordx4 v[232:235], v[66:67], off offset:2144
	global_load_dwordx4 v[236:239], v[68:69], off offset:2144
	global_load_dwordx4 v[240:243], v[64:65], off offset:2144
	s_waitcnt vmcnt(21)
; #define LAS __attribute__((address_space(3)))
; template <int MODE  >
; __device__ __forceinline__ void mini_tile(const Args& a, LAS unsigned char* lds, int tile, int tid) {
;     ...
;     for (int s = 0; s < 8; ++s) {
;         const bf16x8 a1 = *(const bf16x8*)(A1 + 16 * s), b10 = *(const bf16x8*)(B1 + 16 * s), b11 = *(const bf16x8*)(B1 + 32 * LDA + 16 * s);
;         acc[0][0] = __builtin_amdgcn_mfma_f32_32x32x16_bf16(a1, b10, acc[0][0], 0, 0, 0);
;         acc[0][1] = __builtin_amdgcn_mfma_f32_32x32x16_bf16(a1, b11, acc[0][1], 0, 0, 0);
;         if (MODE == 0) {
;             const bf16x8 a2 = *(const bf16x8*)(A2 + 16 * s), b20 = *(const bf16x8*)(B2 + 16 * s), b21 = *(const bf16x8*)(B2 + 32 * LDA + 16 * s);
;             acc[NP - 1][0] = __builtin_amdgcn_mfma_f32_32x32x16_bf16(a2, b20, acc[NP - 1][0], 0, 0, 0);
;             acc[NP - 1][1] = __builtin_amdgcn_mfma_f32_32x32x16_bf16(a2, b21, acc[NP - 1][1], 0, 0, 0);
;         }
;     }
;     LAS float* red = (LAS float*)lds;
; #pragma unroll
;     for (int p = 0; p < NP; ++p)
; #pragma unroll
;         for (int c = 0; c < 2; ++c)
; #pragma unroll
;             for (int i = 0; i < 16; ++i) red[((((wave * NP + p) * 2 + c) * 16 + i) << 6) + lane] = acc[p][c][i];
;     __syncthreads();
	v_mfma_f32_32x32x16_bf16 v[48:63], v[132:135], v[136:139], 0
	v_mfma_f32_32x32x16_bf16 v[32:47], v[132:135], v[140:143], 0
	global_load_dwordx4 v[132:135], v[66:67], off offset:128
	global_load_dwordx4 v[136:139], v[68:69], off offset:128
	global_load_dwordx4 v[140:143], v[64:65], off offset:128
	s_waitcnt vmcnt(21)
	v_mfma_f32_32x32x16_bf16 v[16:31], v[144:147], v[148:151], 0
	v_mfma_f32_32x32x16_bf16 v[0:15], v[144:147], v[152:155], 0
	global_load_dwordx4 v[144:147], v[66:67], off offset:2176
	global_load_dwordx4 v[148:151], v[68:69], off offset:2176
	global_load_dwordx4 v[152:155], v[64:65], off offset:2176
	s_waitcnt vmcnt(21)
	v_mfma_f32_32x32x16_bf16 v[48:63], v[156:159], v[160:163], v[48:63]
	v_mfma_f32_32x32x16_bf16 v[32:47], v[156:159], v[164:167], v[32:47]
	global_load_dwordx4 v[156:159], v[66:67], off offset:160
	global_load_dwordx4 v[160:163], v[68:69], off offset:160
	global_load_dwordx4 v[164:167], v[64:65], off offset:160
	s_waitcnt vmcnt(21)
	v_mfma_f32_32x32x16_bf16 v[16:31], v[168:171], v[172:175], v[16:31]
	v_mfma_f32_32x32x16_bf16 v[0:15], v[168:171], v[176:179], v[0:15]
	global_load_dwordx4 v[168:171], v[66:67], off offset:2208
	global_load_dwordx4 v[172:175], v[68:69], off offset:2208
	global_load_dwordx4 v[176:179], v[64:65], off offset:2208
	s_waitcnt vmcnt(21)
	v_mfma_f32_32x32x16_bf16 v[48:63], v[188:191], v[192:195], v[48:63]
	v_mfma_f32_32x32x16_bf16 v[32:47], v[188:191], v[196:199], v[32:47]
	global_load_dwordx4 v[188:191], v[66:67], off offset:192
	global_load_dwordx4 v[192:195], v[68:69], off offset:192
	global_load_dwordx4 v[196:199], v[64:65], off offset:192
	s_waitcnt vmcnt(21)
	v_mfma_f32_32x32x16_bf16 v[16:31], v[200:203], v[204:207], v[16:31]
	v_mfma_f32_32x32x16_bf16 v[0:15], v[200:203], v[208:211], v[0:15]
	global_load_dwordx4 v[200:203], v[66:67], off offset:2240
	global_load_dwordx4 v[204:207], v[68:69], off offset:2240
	global_load_dwordx4 v[208:211], v[64:65], off offset:2240
	s_waitcnt vmcnt(21)
	v_mfma_f32_32x32x16_bf16 v[48:63], v[220:223], v[224:227], v[48:63]
	v_mfma_f32_32x32x16_bf16 v[32:47], v[220:223], v[228:231], v[32:47]
	global_load_dwordx4 v[220:223], v[66:67], off offset:224
	global_load_dwordx4 v[224:227], v[68:69], off offset:224
	global_load_dwordx4 v[228:231], v[64:65], off offset:224
	s_waitcnt vmcnt(21)
	v_mfma_f32_32x32x16_bf16 v[16:31], v[232:235], v[236:239], v[16:31]
	v_mfma_f32_32x32x16_bf16 v[0:15], v[232:235], v[240:243], v[0:15]
	global_load_dwordx4 v[232:235], v[66:67], off offset:2272
	global_load_dwordx4 v[236:239], v[68:69], off offset:2272
	global_load_dwordx4 v[240:243], v[64:65], off offset:2272
	s_waitcnt vmcnt(21)
	v_mfma_f32_32x32x16_bf16 v[48:63], v[132:135], v[136:139], v[48:63]
	v_mfma_f32_32x32x16_bf16 v[32:47], v[132:135], v[140:143], v[32:47]
	s_waitcnt vmcnt(18)
	v_mfma_f32_32x32x16_bf16 v[16:31], v[144:147], v[148:151], v[16:31]
	v_mfma_f32_32x32x16_bf16 v[0:15], v[144:147], v[152:155], v[0:15]
	s_waitcnt vmcnt(15)
	v_mfma_f32_32x32x16_bf16 v[48:63], v[156:159], v[160:163], v[48:63]
	v_mfma_f32_32x32x16_bf16 v[32:47], v[156:159], v[164:167], v[32:47]
	s_waitcnt vmcnt(12)
	v_mfma_f32_32x32x16_bf16 v[16:31], v[168:171], v[172:175], v[16:31]
	v_mfma_f32_32x32x16_bf16 v[0:15], v[168:171], v[176:179], v[0:15]
	s_waitcnt vmcnt(9)
	v_mfma_f32_32x32x16_bf16 v[48:63], v[188:191], v[192:195], v[48:63]
	v_mfma_f32_32x32x16_bf16 v[32:47], v[188:191], v[196:199], v[32:47]
	s_waitcnt vmcnt(6)
	v_mfma_f32_32x32x16_bf16 v[16:31], v[200:203], v[204:207], v[16:31]
	v_mfma_f32_32x32x16_bf16 v[0:15], v[200:203], v[208:211], v[0:15]
	s_waitcnt vmcnt(3)
	v_mfma_f32_32x32x16_bf16 v[48:63], v[220:223], v[224:227], v[48:63]
	v_mfma_f32_32x32x16_bf16 v[32:47], v[220:223], v[228:231], v[32:47]
	s_waitcnt vmcnt(0)
	v_mfma_f32_32x32x16_bf16 v[16:31], v[232:235], v[236:239], v[16:31]
	v_mfma_f32_32x32x16_bf16 v[0:15], v[232:235], v[240:243], v[0:15]
	v_lshl_add_u32 v64, s24, 14, v71
	s_nop 11
	ds_write2st64_b32 v64, v48, v49 offset1:1
	ds_write2st64_b32 v64, v50, v51 offset0:2 offset1:3
	ds_write2st64_b32 v64, v52, v53 offset0:4 offset1:5
	ds_write2st64_b32 v64, v54, v55 offset0:6 offset1:7
	ds_write2st64_b32 v64, v56, v57 offset0:8 offset1:9
	ds_write2st64_b32 v64, v58, v59 offset0:10 offset1:11
	ds_write2st64_b32 v64, v60, v61 offset0:12 offset1:13
	ds_write2st64_b32 v64, v62, v63 offset0:14 offset1:15
	ds_write2st64_b32 v64, v32, v33 offset0:16 offset1:17
	ds_write2st64_b32 v64, v34, v35 offset0:18 offset1:19
	ds_write2st64_b32 v64, v36, v37 offset0:20 offset1:21
	ds_write2st64_b32 v64, v38, v39 offset0:22 offset1:23
	ds_write2st64_b32 v64, v40, v41 offset0:24 offset1:25
	ds_write2st64_b32 v64, v42, v43 offset0:26 offset1:27
	ds_write2st64_b32 v64, v44, v45 offset0:28 offset1:29
	ds_write2st64_b32 v64, v46, v47 offset0:30 offset1:31
	ds_write2st64_b32 v64, v16, v17 offset0:32 offset1:33
	ds_write2st64_b32 v64, v18, v19 offset0:34 offset1:35
	ds_write2st64_b32 v64, v20, v21 offset0:36 offset1:37
	ds_write2st64_b32 v64, v22, v23 offset0:38 offset1:39
	ds_write2st64_b32 v64, v24, v25 offset0:40 offset1:41
	ds_write2st64_b32 v64, v26, v27 offset0:42 offset1:43
	ds_write2st64_b32 v64, v28, v29 offset0:44 offset1:45
	ds_write2st64_b32 v64, v30, v31 offset0:46 offset1:47
	ds_write2st64_b32 v64, v0, v1 offset0:48 offset1:49
	ds_write2st64_b32 v64, v2, v3 offset0:50 offset1:51
	ds_write2st64_b32 v64, v4, v5 offset0:52 offset1:53
	ds_write2st64_b32 v64, v6, v7 offset0:54 offset1:55
	ds_write2st64_b32 v64, v8, v9 offset0:56 offset1:57
	ds_write2st64_b32 v64, v10, v11 offset0:58 offset1:59
	ds_write2st64_b32 v64, v12, v13 offset0:60 offset1:61
	ds_write2st64_b32 v64, v14, v15 offset0:62 offset1:63
	s_waitcnt lgkmcnt(0)
	s_barrier
; __device__ __forceinline__ unsigned pk2(float lo, float hi) { unsigned r; asm("v_cvt_pk_bf16_f32 %0, %1, %2" : "=v"(r) : "v"(lo), "v"(hi)); return r; }
; __device__ __forceinline__ float bf1(bf16_t u) { return __uint_as_float(((unsigned)u) << 16); }
; template <int MODE  >
; __device__ __forceinline__ void mini_tile(const Args& a, LAS unsigned char* lds, int tile, int tid) {
;     ...
; #pragma unroll
;     for (int j = 0; j < 4; ++j) {
;         const int e = tid + 512 * j, c = e >> 10, i = (e >> 6) & 15, l = e & 63;
;         float s1 = 0.f, s2 = 0.f;
; #pragma unroll
;         for (int w = 0; w < 8; ++w) { s1 += red[((((w * NP + 0) * 2 + c) * 16 + i) << 6) + l]; if (MODE == 0) s2 += red[((((w * NP + NP - 1) * 2 + c) * 16 + i) << 6) + l]; }
;         const int row = R0 + 8 * (i >> 2) + 4 * (l >> 5) + (i & 3), col = C0 + 32 * c + (l & 31);
;         if (MODE == 0) {
;             const size_t o = (size_t)row * DM + col;
;             const float m = bf1(PA[6 * (size_t)MPAD * DM + o]) * s1 + bf1(PA[7 * (size_t)MPAD * DM + o]) * s2;
;             ((bf16_t*)(a.ws + WS_MM))[o] = (bf16_t)(pk2(m, m) & 0xffffu);
	ds_read2st64_b32 v[0:1], v72 offset1:32
	s_waitcnt lgkmcnt(0)
	v_add_f32_e32 v2, 0, v0
	v_add_f32_e32 v3, 0, v1
	ds_read2st64_b32 v[0:1], v72 offset0:64 offset1:96
	s_waitcnt lgkmcnt(0)
	v_add_f32_e32 v2, v2, v0
	v_add_f32_e32 v3, v3, v1
	ds_read2st64_b32 v[0:1], v72 offset0:128 offset1:160
	s_waitcnt lgkmcnt(0)
	v_add_f32_e32 v2, v2, v0
	v_add_f32_e32 v3, v3, v1
	ds_read2st64_b32 v[0:1], v72 offset0:192 offset1:224
	s_waitcnt lgkmcnt(0)
	v_add_f32_e32 v0, v2, v0
	ds_read_b32 v2, v100
	v_add_f32_e32 v1, v3, v1
	s_waitcnt lgkmcnt(0)
	v_add_f32_e32 v0, v0, v2
	ds_read_b32 v2, v73
	s_waitcnt lgkmcnt(0)
	v_add_f32_e32 v1, v1, v2
	ds_read_b32 v2, v101
	s_waitcnt lgkmcnt(0)
	v_add_f32_e32 v0, v0, v2
	ds_read_b32 v2, v74
	s_waitcnt lgkmcnt(0)
	v_add_f32_e32 v1, v1, v2
	ds_read_b32 v2, v102
	s_waitcnt lgkmcnt(0)
	v_add_f32_e32 v0, v0, v2
	ds_read_b32 v2, v75
	s_waitcnt lgkmcnt(0)
	v_add_f32_e32 v1, v1, v2
	ds_read_b32 v2, v103
	s_waitcnt lgkmcnt(0)
	v_add_f32_e32 v6, v0, v2
	ds_read_b32 v0, v76
	v_add_u32_e32 v2, v116, v78
	v_ashrrev_i32_e32 v3, 31, v2
	s_waitcnt lgkmcnt(0)
	v_add_f32_e32 v7, v1, v0
	v_or_b32_e32 v0, s23, v77
	v_ashrrev_i32_e32 v1, 31, v0
	v_lshlrev_b64 v[0:1], 10, v[0:1]
	v_lshl_add_u64 v[0:1], v[0:1], 0, v[2:3]
	v_lshlrev_b64 v[0:1], 1, v[0:1]
	v_lshl_add_u64 v[2:3], s[74:75], 0, v[0:1]
	v_add_co_u32_e32 v4, vcc, s3, v2
	v_lshl_add_u64 v[0:1], s[88:89], 0, v[0:1]
	s_nop 0
	v_addc_co_u32_e32 v5, vcc, 0, v3, vcc
	v_add_co_u32_e32 v2, vcc, s26, v2
	global_load_ushort v4, v[4:5], off
	s_nop 0
	v_addc_co_u32_e32 v3, vcc, 0, v3, vcc
	global_load_ushort v2, v[2:3], off
	s_waitcnt vmcnt(1)
	v_lshlrev_b32_e32 v4, 16, v4
	s_waitcnt vmcnt(0)
	v_lshlrev_b32_e32 v2, 16, v2
	v_mul_f32_e32 v2, v7, v2
	v_fmac_f32_e32 v2, v6, v4
	v_cvt_pk_bf16_f32 v2, v2, v2
	global_store_short v[0:1], v2, off
	ds_read2st64_b32 v[0:1], v79 offset1:32
	s_waitcnt lgkmcnt(0)
	v_add_f32_e32 v2, 0, v0
	v_add_f32_e32 v3, 0, v1
	ds_read2st64_b32 v[0:1], v79 offset0:64 offset1:96
	s_waitcnt lgkmcnt(0)
	v_add_f32_e32 v2, v2, v0
	v_add_f32_e32 v3, v3, v1
	ds_read2st64_b32 v[0:1], v79 offset0:128 offset1:160
	s_waitcnt lgkmcnt(0)
	v_add_f32_e32 v2, v2, v0
	v_add_f32_e32 v3, v3, v1
	ds_read2st64_b32 v[0:1], v79 offset0:192 offset1:224
	s_waitcnt lgkmcnt(0)
	v_add_f32_e32 v0, v2, v0
	ds_read_b32 v2, v104
	v_add_f32_e32 v1, v3, v1
	s_waitcnt lgkmcnt(0)
	v_add_f32_e32 v0, v0, v2
	ds_read_b32 v2, v80
	s_waitcnt lgkmcnt(0)
	v_add_f32_e32 v1, v1, v2
	ds_read_b32 v2, v105
	s_waitcnt lgkmcnt(0)
	v_add_f32_e32 v0, v0, v2
	ds_read_b32 v2, v81
	s_waitcnt lgkmcnt(0)
	v_add_f32_e32 v1, v1, v2
	ds_read_b32 v2, v106
	s_waitcnt lgkmcnt(0)
	v_add_f32_e32 v0, v0, v2
	ds_read_b32 v2, v82
	s_waitcnt lgkmcnt(0)
	v_add_f32_e32 v1, v1, v2
	ds_read_b32 v2, v107
	s_waitcnt lgkmcnt(0)
	v_add_f32_e32 v6, v0, v2
	ds_read_b32 v0, v83
	v_add_u32_e32 v2, v116, v85
	v_ashrrev_i32_e32 v3, 31, v2
	s_waitcnt lgkmcnt(0)
	v_add_f32_e32 v7, v1, v0
	v_or_b32_e32 v0, s23, v84
	v_ashrrev_i32_e32 v1, 31, v0
	v_lshlrev_b64 v[0:1], 10, v[0:1]
	v_lshl_add_u64 v[0:1], v[0:1], 0, v[2:3]
	v_lshlrev_b64 v[0:1], 1, v[0:1]
	v_lshl_add_u64 v[2:3], s[74:75], 0, v[0:1]
	v_add_co_u32_e32 v4, vcc, s3, v2
	v_lshl_add_u64 v[0:1], s[88:89], 0, v[0:1]
	s_nop 0
	v_addc_co_u32_e32 v5, vcc, 0, v3, vcc
	v_add_co_u32_e32 v2, vcc, s26, v2
	global_load_ushort v4, v[4:5], off
	s_nop 0
	v_addc_co_u32_e32 v3, vcc, 0, v3, vcc
	global_load_ushort v2, v[2:3], off
	s_waitcnt vmcnt(1)
	v_lshlrev_b32_e32 v4, 16, v4
	s_waitcnt vmcnt(0)
	v_lshlrev_b32_e32 v2, 16, v2
	v_mul_f32_e32 v2, v7, v2
	v_fmac_f32_e32 v2, v6, v4
	v_cvt_pk_bf16_f32 v2, v2, v2
	global_store_short v[0:1], v2, off
	ds_read2st64_b32 v[0:1], v86 offset1:32
	s_waitcnt lgkmcnt(0)
; __device__ __forceinline__ unsigned pk2(float lo, float hi) { unsigned r; asm("v_cvt_pk_bf16_f32 %0, %1, %2" : "=v"(r) : "v"(lo), "v"(hi)); return r; }
; __device__ __forceinline__ float bf1(bf16_t u) { return __uint_as_float(((unsigned)u) << 16); }
; template <int MODE  >
; __device__ __forceinline__ void mini_tile(const Args& a, LAS unsigned char* lds, int tile, int tid) {
;     ...
; #pragma unroll
;     for (int j = 0; j < 4; ++j) {
;         const int e = tid + 512 * j, c = e >> 10, i = (e >> 6) & 15, l = e & 63;
;         float s1 = 0.f, s2 = 0.f;
; #pragma unroll
;         for (int w = 0; w < 8; ++w) { s1 += red[((((w * NP + 0) * 2 + c) * 16 + i) << 6) + l]; if (MODE == 0) s2 += red[((((w * NP + NP - 1) * 2 + c) * 16 + i) << 6) + l]; }
;         const int row = R0 + 8 * (i >> 2) + 4 * (l >> 5) + (i & 3), col = C0 + 32 * c + (l & 31);
;         if (MODE == 0) {
;             const size_t o = (size_t)row * DM + col;
;             const float m = bf1(PA[6 * (size_t)MPAD * DM + o]) * s1 + bf1(PA[7 * (size_t)MPAD * DM + o]) * s2;
;             ((bf16_t*)(a.ws + WS_MM))[o] = (bf16_t)(pk2(m, m) & 0xffffu);
;         } else {
;             if (row < MP) { const int b = row / TP, t = row - b * TP; if (t >= NMETA) { const size_t o = ((size_t)b * SEQ + (t - NMETA)) * DM + col; a.out[O_YP + o] = a.xp[o] + s1; } }
;             else if (row < MV) { const size_t o = (size_t)(row - MP) * DM + col; a.out[O_YS + o] = a.xs[o] + s1; }
;         }
;     }
;     __syncthreads();
; __global__ __launch_bounds__(512, 2) void fwd_mega(Args a0_) {
;     ...
;             pg8::gemm_phase<EpiGateF, true, true>(lds, g, S, E, tid);
	v_add_f32_e32 v2, 0, v0
	v_add_f32_e32 v3, 0, v1
	ds_read2st64_b32 v[0:1], v86 offset0:64 offset1:96
	s_waitcnt lgkmcnt(0)
	v_add_f32_e32 v2, v2, v0
	v_add_f32_e32 v3, v3, v1
	ds_read2st64_b32 v[0:1], v86 offset0:128 offset1:160
	s_waitcnt lgkmcnt(0)
	v_add_f32_e32 v2, v2, v0
	v_add_f32_e32 v3, v3, v1
	ds_read2st64_b32 v[0:1], v86 offset0:192 offset1:224
	s_waitcnt lgkmcnt(0)
	v_add_f32_e32 v0, v2, v0
	ds_read_b32 v2, v108
	v_add_f32_e32 v1, v3, v1
	s_waitcnt lgkmcnt(0)
	v_add_f32_e32 v0, v0, v2
	ds_read_b32 v2, v87
	s_waitcnt lgkmcnt(0)
	v_add_f32_e32 v1, v1, v2
	ds_read_b32 v2, v109
	s_waitcnt lgkmcnt(0)
	v_add_f32_e32 v0, v0, v2
	ds_read_b32 v2, v88
	s_waitcnt lgkmcnt(0)
	v_add_f32_e32 v1, v1, v2
	ds_read_b32 v2, v110
	s_waitcnt lgkmcnt(0)
	v_add_f32_e32 v0, v0, v2
	ds_read_b32 v2, v89
	s_waitcnt lgkmcnt(0)
	v_add_f32_e32 v1, v1, v2
	ds_read_b32 v2, v111
	s_waitcnt lgkmcnt(0)
	v_add_f32_e32 v6, v0, v2
	ds_read_b32 v0, v90
	v_add_u32_e32 v2, v116, v92
	v_ashrrev_i32_e32 v3, 31, v2
	s_waitcnt lgkmcnt(0)
	v_add_f32_e32 v7, v1, v0
	v_or_b32_e32 v0, s23, v91
	v_ashrrev_i32_e32 v1, 31, v0
	v_lshlrev_b64 v[0:1], 10, v[0:1]
	v_lshl_add_u64 v[0:1], v[0:1], 0, v[2:3]
	v_lshlrev_b64 v[0:1], 1, v[0:1]
	v_lshl_add_u64 v[2:3], s[74:75], 0, v[0:1]
	v_add_co_u32_e32 v4, vcc, s3, v2
	v_lshl_add_u64 v[0:1], s[88:89], 0, v[0:1]
	s_nop 0
	v_addc_co_u32_e32 v5, vcc, 0, v3, vcc
	v_add_co_u32_e32 v2, vcc, s26, v2
	global_load_ushort v4, v[4:5], off
	s_nop 0
	v_addc_co_u32_e32 v3, vcc, 0, v3, vcc
	global_load_ushort v2, v[2:3], off
	s_waitcnt vmcnt(1)
	v_lshlrev_b32_e32 v4, 16, v4
	s_waitcnt vmcnt(0)
	v_lshlrev_b32_e32 v2, 16, v2
	v_mul_f32_e32 v2, v7, v2
	v_fmac_f32_e32 v2, v6, v4
	v_cvt_pk_bf16_f32 v2, v2, v2
	global_store_short v[0:1], v2, off
	ds_read2st64_b32 v[0:1], v93 offset1:32
	s_waitcnt lgkmcnt(0)
	v_add_f32_e32 v2, 0, v0
	v_add_f32_e32 v3, 0, v1
	ds_read2st64_b32 v[0:1], v93 offset0:64 offset1:96
	s_waitcnt lgkmcnt(0)
	v_add_f32_e32 v2, v2, v0
	v_add_f32_e32 v3, v3, v1
	ds_read2st64_b32 v[0:1], v93 offset0:128 offset1:160
	s_waitcnt lgkmcnt(0)
	v_add_f32_e32 v2, v2, v0
	v_add_f32_e32 v3, v3, v1
	ds_read2st64_b32 v[0:1], v93 offset0:192 offset1:224
	s_waitcnt lgkmcnt(0)
	v_add_f32_e32 v0, v2, v0
	ds_read_b32 v2, v112
	v_add_f32_e32 v1, v3, v1
	s_waitcnt lgkmcnt(0)
	v_add_f32_e32 v0, v0, v2
	ds_read_b32 v2, v94
	s_waitcnt lgkmcnt(0)
	v_add_f32_e32 v1, v1, v2
	ds_read_b32 v2, v113
	s_waitcnt lgkmcnt(0)
	v_add_f32_e32 v0, v0, v2
	ds_read_b32 v2, v95
	s_waitcnt lgkmcnt(0)
	v_add_f32_e32 v1, v1, v2
	ds_read_b32 v2, v114
	s_waitcnt lgkmcnt(0)
	v_add_f32_e32 v0, v0, v2
	ds_read_b32 v2, v96
	s_waitcnt lgkmcnt(0)
	v_add_f32_e32 v1, v1, v2
	ds_read_b32 v2, v115
	s_waitcnt lgkmcnt(0)
	v_add_f32_e32 v6, v0, v2
	ds_read_b32 v0, v97
	v_add_u32_e32 v2, v116, v99
	v_ashrrev_i32_e32 v3, 31, v2
	s_waitcnt lgkmcnt(0)
	v_add_f32_e32 v7, v1, v0
	v_or_b32_e32 v0, s23, v98
	v_ashrrev_i32_e32 v1, 31, v0
	v_lshlrev_b64 v[0:1], 10, v[0:1]
	v_lshl_add_u64 v[0:1], v[0:1], 0, v[2:3]
	v_lshlrev_b64 v[0:1], 1, v[0:1]
	v_lshl_add_u64 v[2:3], s[74:75], 0, v[0:1]
	v_add_co_u32_e32 v4, vcc, s3, v2
	v_lshl_add_u64 v[0:1], s[88:89], 0, v[0:1]
	s_nop 0
	v_addc_co_u32_e32 v5, vcc, 0, v3, vcc
	v_add_co_u32_e32 v2, vcc, s26, v2
	global_load_ushort v4, v[4:5], off
	s_nop 0
	v_addc_co_u32_e32 v3, vcc, 0, v3, vcc
	global_load_ushort v2, v[2:3], off
	s_waitcnt vmcnt(1)
	v_lshlrev_b32_e32 v4, 16, v4
	s_waitcnt vmcnt(0)
	v_lshlrev_b32_e32 v2, 16, v2
	v_mul_f32_e32 v2, v7, v2
	v_fmac_f32_e32 v2, v6, v4
	v_cvt_pk_bf16_f32 v2, v2, v2
	global_store_short v[0:1], v2, off
	s_barrier
	s_cbranch_scc0 .LBB0_50
	s_branch .Lsb_gemm4
